# grid syncs 2-6: XCC-hierarchical barrier (per-XCC arrival counter, one L2 write-back per XCC, cross-XCC counter) instead of the flat cooperative-groups software barrier; falls back when grid != 256
# speedup vs baseline: 1.0144x; 1.0144x over previous
; #define PG8_LAS __attribute__((address_space(3)))
; __global__ void __launch_bounds__(512, 2) mega_fwd(Args args) {
;     ...
;     P.x = args.in[0]; P.w_in = args.in[1]; P.kvg = args.in[2]; P.w_uv = args.in[3]; P.w_a = args.in[4]; P.conv_w = args.in[5]; P.conv_b = args.in[6];
;     P.wga = args.in[7]; P.bga = args.in[8]; P.wgx = args.in[9]; P.bgx = args.in[10]; P.lam = args.in[11]; P.w_b = args.in[12]; P.relb = args.in[13];
;     P.w_o = args.in[14]; P.ln_g = args.in[15]; P.ln_b = args.in[16]; P.out = args.out; P.ws = args.ws;
;     unsigned char* ws = args.ws;
;     P.WinT = (bf16_t*)(ws + WS_WIN); P.WuvT = (bf16_t*)(ws + WS_WUV); P.WaT = (bf16_t*)(ws + WS_WA); P.WbT = (bf16_t*)(ws + WS_WB); P.WoT = (bf16_t*)(ws + WS_WO);
;     P.WgaT = (bf16_t*)(ws + WS_WGA); P.WgxT = (bf16_t*)(ws + WS_WGX); P.QL = (bf16_t*)(ws + WS_QL); P.CKV = (bf16_t*)(ws + WS_CKV); P.AG = (bf16_t*)(ws + WS_AG);
;     P.QI = (bf16_t*)(ws + WS_QI); P.KI = (bf16_t*)(ws + WS_KI); P.XR = (bf16_t*)(ws + WS_XR); P.RG = (bf16_t*)(ws + WS_RG); P.GB = (bf16_t*)(ws + WS_GB);
;     P.XB = (bf16_t*)args.out; P.GA = (bf16_t*)args.out + (size_t)M * D;
;     P.WI = (float*)(ws + WS_WI); P.CKVF = (float*)(ws + WS_CKVF); P.BT = (float*)(ws + WS_BT);
;     unsigned* ctl = (unsigned*)(ws + WS_CTL);
;     PG8_LAS unsigned char* ldsl = (PG8_LAS unsigned char*)lds;
;     const int lo = args.ph_lo, hi = args.ph_hi;
;     ...
;     if (IN(0)) { if (blockIdx.x == 0 && tid < 4) ctl[64 * tid] = 0u; p0_prologue(P, lds, tid, G); }
_Z8mega_fwd4Args:
	s_load_dwordx16 s[36:51], s[0:1], 0x0
	s_load_dwordx8 s[52:59], s[0:1], 0x80
	s_load_dwordx16 s[16:31], s[0:1], 0x40
	s_add_u32 s4, s0, 0xa0
	s_addc_u32 s5, s1, 0
	s_load_dword s34, s[0:1], 0xa0
	s_waitcnt lgkmcnt(0)
	s_add_u32 s72, s56, 0x200000
	s_addc_u32 s73, s57, 0
	s_add_u32 s68, s56, 0x4000000
	s_addc_u32 s69, s57, 0
	s_add_u32 s66, s56, 0x4200000
	s_addc_u32 s67, s57, 0
	v_writelane_b32 v252, s4, 0
	s_add_u32 s0, s56, 0x4a00000
	s_addc_u32 s1, s57, 0
	v_writelane_b32 v252, s5, 1
	v_writelane_b32 v252, s0, 2
	v_and_b32_e32 v188, 0x3ff, v0
	s_nop 0
	v_writelane_b32 v252, s1, 3
	s_add_u32 s0, s56, 0x5200000
	s_addc_u32 s1, s57, 0
	s_add_u32 s64, s56, 0x5a00000
	s_addc_u32 s65, s57, 0
	s_add_u32 s70, s56, 0x5a80000
	s_addc_u32 s71, s57, 0
	v_writelane_b32 v252, s0, 4
	s_cmp_lt_i32 s58, 1
	s_nop 0
	v_writelane_b32 v252, s1, 5
	s_cselect_b64 s[0:1], -1, 0
	s_cmp_gt_i32 s59, 0
	s_cselect_b64 s[4:5], -1, 0
	s_and_b64 s[4:5], s[0:1], s[4:5]
	s_andn2_b64 vcc, exec, s[4:5]
	s_cbranch_vccnz .LBB0_110
	s_cmp_eq_u32 s2, 0
	s_cselect_b64 s[0:1], -1, 0
	v_cmp_gt_u32_e32 vcc, 64, v188
	s_and_b64 s[6:7], s[0:1], vcc
	s_and_saveexec_b64 s[0:1], s[6:7]
	s_cbranch_execz .LBB0_3
	v_lshlrev_b32_e32 v1, 8, v188
	v_mov_b32_e32 v2, 0
	global_store_dword v1, v2, s[56:57]

; #define SEAM(k) do { if (IN(k) && IN((k) + 1)) grid.sync(); } while (0)
; __global__ void __launch_bounds__(512, 2) mega_fwd(Args args) {
;     ...
;     SEAM(1);
.LBB0_438:
	s_cmp_gt_i32 s59, 2
	s_cselect_b64 s[0:1], -1, 0
	s_and_b64 s[4:5], s[80:81], s[0:1]
	s_andn2_b64 vcc, exec, s[4:5]
	s_cbranch_vccnz .LBB0_450
	v_or_b32_e32 v0, v206, v189
	s_movk_i32 s3, 0x3ff
	v_and_or_b32 v0, v0, s3, v188
	v_cmp_eq_u32_e32 vcc, 0, v0
	s_waitcnt vmcnt(0)
	s_barrier
	s_and_saveexec_b64 s[4:5], vcc
	s_cbranch_execz .LBB0_449
	v_readlane_b32 s6, v252, 0
	v_readlane_b32 s7, v252, 1
	s_load_dword s8, s[6:7], 0x0
	s_sub_u32 s6, s6, 16
	s_subb_u32 s7, s7, 0
	s_waitcnt lgkmcnt(0)
	s_cmp_lg_u32 s8, 0x100
	s_cbranch_scc1 .Lgs2_cg
	s_load_dwordx2 s[6:7], s[6:7], 0x0
	s_getreg_b32 s3, hwreg(HW_REG_XCC_ID, 0, 4)
	v_mov_b32_e32 v3, 1
	s_mov_b32 s12, 0
	s_lshl_b32 s3, s3, 8
	v_mov_b32_e32 v2, s3
	v_or_b32_e32 v2, 0x1000, v2
	s_waitcnt lgkmcnt(0)
	global_atomic_add v0, v2, v3, s[6:7] sc0
	s_waitcnt vmcnt(0)
	v_readfirstlane_b32 s8, v0
	v_xor_b32_e32 v2, 0x3000, v2
	s_and_b32 s9, s8, 31
	s_lshr_b32 s10, s8, 5
	s_cmp_eq_u32 s9, 31
	s_cbranch_scc0 .Lgs2_wl
	buffer_wbl2 sc1
	s_waitcnt vmcnt(0)
	v_mov_b32_e32 v1, 0x3000
	global_atomic_add v0, v1, v3, s[6:7] sc0
	s_waitcnt vmcnt(0)
	v_readfirstlane_b32 s8, v0
	v_mov_b32_e32 v1, 0x3100
	s_and_b32 s9, s8, 7
	s_lshr_b32 s11, s8, 3
	s_cmp_eq_u32 s9, 7
	s_cbranch_scc0 .Lgs2_wt
	global_atomic_add v1, v3, s[6:7]
	s_branch .Lgs2_td
.Lgs2_wt:
	s_add_u32 s12, s12, 1
	s_cmp_gt_u32 s12, 0x3fff
	s_cbranch_scc1 .Lgs2_td
	s_sleep 2
	global_load_dword v0, v1, s[6:7] sc1
	s_waitcnt vmcnt(0)
	v_readfirstlane_b32 s8, v0
	s_nop 0
	s_cmp_eq_u32 s8, s11
	s_cbranch_scc1 .Lgs2_wt
.Lgs2_td:
	buffer_inv sc1
	global_atomic_add v2, v3, s[6:7]
	s_waitcnt vmcnt(0)
	s_branch .LBB0_449
.Lgs2_wl:
	s_add_u32 s12, s12, 1
	s_cmp_gt_u32 s12, 0x3fff
	s_cbranch_scc1 .Lgs2_wx
	s_sleep 2
	global_load_dword v0, v2, s[6:7] sc1
	s_waitcnt vmcnt(0)
	v_readfirstlane_b32 s8, v0
	s_nop 0
	s_cmp_eq_u32 s8, s10
	s_cbranch_scc1 .Lgs2_wl
.Lgs2_wx:
	buffer_inv sc1
	s_waitcnt vmcnt(0)
	s_branch .LBB0_449
	s_nop 0
	s_nop 0
	s_nop 0
	s_nop 0
	s_nop 0
	s_nop 0
	s_nop 0
	s_nop 0
	s_nop 0
	s_nop 0
	s_nop 0
	s_nop 0
.Lgs2_cg:
	v_readlane_b32 s6, v252, 0
	v_readlane_b32 s7, v252, 1
	buffer_wbl2 sc1
	s_load_dwordx2 s[6:7], s[6:7], 0x58
	v_mov_b32_e32 v2, 0
	s_mov_b64 s[8:9], exec
	v_mbcnt_lo_u32_b32 v1, s8, 0
	v_mbcnt_hi_u32_b32 v1, s9, v1
	s_waitcnt lgkmcnt(0)
	global_load_dword v0, v2, s[6:7] offset:40
	v_cmp_eq_u32_e32 vcc, 0, v1
	s_and_saveexec_b64 s[10:11], vcc
	s_cbranch_execz .LBB0_442
	s_bcnt1_i32_b64 s3, s[8:9]
	v_mov_b32_e32 v3, s3
	global_atomic_add v3, v2, v3, s[6:7] offset:32 sc0

; #define SEAM(k) do { if (IN(k) && IN((k) + 1)) grid.sync(); } while (0)
; __global__ void __launch_bounds__(512, 2) mega_fwd(Args args) {
;     ...
;     SEAM(2);
.LBB0_933:
	s_cmp_gt_i32 s59, 3
	s_cselect_b64 s[0:1], -1, 0
	s_and_b64 s[4:5], s[40:41], s[0:1]
	s_andn2_b64 vcc, exec, s[4:5]
	s_cbranch_vccnz .LBB0_945
	v_or_b32_e32 v0, v206, v189
	s_movk_i32 s3, 0x3ff
	v_and_or_b32 v0, v0, s3, v188
	v_cmp_eq_u32_e32 vcc, 0, v0
	s_waitcnt vmcnt(0)
	s_barrier
	s_and_saveexec_b64 s[4:5], vcc
	s_cbranch_execz .LBB0_944
	v_readlane_b32 s6, v252, 0
	v_readlane_b32 s7, v252, 1
	s_load_dword s8, s[6:7], 0x0
	s_sub_u32 s6, s6, 16
	s_subb_u32 s7, s7, 0
	s_waitcnt lgkmcnt(0)
	s_cmp_lg_u32 s8, 0x100
	s_cbranch_scc1 .Lgs3_cg
	s_load_dwordx2 s[6:7], s[6:7], 0x0
	s_getreg_b32 s3, hwreg(HW_REG_XCC_ID, 0, 4)
	v_mov_b32_e32 v3, 1
	s_mov_b32 s12, 0
	s_lshl_b32 s3, s3, 8
	v_mov_b32_e32 v2, s3
	v_or_b32_e32 v2, 0x1000, v2
	s_waitcnt lgkmcnt(0)
	global_atomic_add v0, v2, v3, s[6:7] sc0
	s_waitcnt vmcnt(0)
	v_readfirstlane_b32 s8, v0
	v_xor_b32_e32 v2, 0x3000, v2
	s_and_b32 s9, s8, 31
	s_lshr_b32 s10, s8, 5
	s_cmp_eq_u32 s9, 31
	s_cbranch_scc0 .Lgs3_wl
	buffer_wbl2 sc1
	s_waitcnt vmcnt(0)
	v_mov_b32_e32 v1, 0x3000
	global_atomic_add v0, v1, v3, s[6:7] sc0
	s_waitcnt vmcnt(0)
	v_readfirstlane_b32 s8, v0
	v_mov_b32_e32 v1, 0x3100
	s_and_b32 s9, s8, 7
	s_lshr_b32 s11, s8, 3
	s_cmp_eq_u32 s9, 7
	s_cbranch_scc0 .Lgs3_wt
	global_atomic_add v1, v3, s[6:7]
	s_branch .Lgs3_td

; #define SEAM(k) do { if (IN(k) && IN((k) + 1)) grid.sync(); } while (0)
; __global__ void __launch_bounds__(512, 2) mega_fwd(Args args) {
;     ...
;     SEAM(3);
.LBB0_970:
	s_cmp_gt_i32 s59, 4
	s_cselect_b64 s[0:1], -1, 0
	s_and_b64 s[4:5], s[4:5], s[0:1]
	s_andn2_b64 vcc, exec, s[4:5]
	s_cbranch_vccnz .LBB0_982
	v_or_b32_e32 v0, v206, v189
	s_movk_i32 s3, 0x3ff
	v_and_or_b32 v0, v0, s3, v188
	v_cmp_eq_u32_e32 vcc, 0, v0
	s_waitcnt vmcnt(0)
	s_barrier
	s_and_saveexec_b64 s[4:5], vcc
	s_cbranch_execz .LBB0_981
	v_readlane_b32 s6, v252, 0
	v_readlane_b32 s7, v252, 1
	s_load_dword s8, s[6:7], 0x0
	s_sub_u32 s6, s6, 16
	s_subb_u32 s7, s7, 0
	s_waitcnt lgkmcnt(0)
	s_cmp_lg_u32 s8, 0x100
	s_cbranch_scc1 .Lgs4_cg
	s_load_dwordx2 s[6:7], s[6:7], 0x0
	s_getreg_b32 s3, hwreg(HW_REG_XCC_ID, 0, 4)
	v_mov_b32_e32 v3, 1
	s_mov_b32 s12, 0
	s_lshl_b32 s3, s3, 8
	v_mov_b32_e32 v2, s3
	v_or_b32_e32 v2, 0x1000, v2
	s_waitcnt lgkmcnt(0)
	global_atomic_add v0, v2, v3, s[6:7] sc0
	s_waitcnt vmcnt(0)
	v_readfirstlane_b32 s8, v0
	v_xor_b32_e32 v2, 0x3000, v2
	s_and_b32 s9, s8, 31
	s_lshr_b32 s10, s8, 5
	s_cmp_eq_u32 s9, 31
	s_cbranch_scc0 .Lgs4_wl
	buffer_wbl2 sc1
	s_waitcnt vmcnt(0)
	v_mov_b32_e32 v1, 0x3000
	global_atomic_add v0, v1, v3, s[6:7] sc0
	s_waitcnt vmcnt(0)
	v_readfirstlane_b32 s8, v0
	v_mov_b32_e32 v1, 0x3100
	s_and_b32 s9, s8, 7
	s_lshr_b32 s11, s8, 3
	s_cmp_eq_u32 s9, 7
	s_cbranch_scc0 .Lgs4_wt
	global_atomic_add v1, v3, s[6:7]
	s_branch .Lgs4_td

; #define SEAM(k) do { if (IN(k) && IN((k) + 1)) grid.sync(); } while (0)
; __global__ void __launch_bounds__(512, 2) mega_fwd(Args args) {
;     ...
;     SEAM(4);
.LBB0_1031:
	s_cmp_gt_i32 s59, 5
	s_cselect_b64 s[0:1], -1, 0
	s_and_b64 s[4:5], s[4:5], s[0:1]
	s_andn2_b64 vcc, exec, s[4:5]
	s_cbranch_vccnz .LBB0_1043
	v_or_b32_e32 v0, v206, v189
	s_movk_i32 s3, 0x3ff
	v_and_or_b32 v0, v0, s3, v188
	v_cmp_eq_u32_e32 vcc, 0, v0
	s_waitcnt vmcnt(0)
	s_barrier
	s_and_saveexec_b64 s[4:5], vcc
	s_cbranch_execz .LBB0_1042
	v_readlane_b32 s6, v252, 0
	v_readlane_b32 s7, v252, 1
	s_load_dword s8, s[6:7], 0x0
	s_sub_u32 s6, s6, 16
	s_subb_u32 s7, s7, 0
	s_waitcnt lgkmcnt(0)
	s_cmp_lg_u32 s8, 0x100
	s_cbranch_scc1 .Lgs5_cg
	s_load_dwordx2 s[6:7], s[6:7], 0x0
	s_getreg_b32 s3, hwreg(HW_REG_XCC_ID, 0, 4)
	v_mov_b32_e32 v3, 1
	s_mov_b32 s12, 0
	s_lshl_b32 s3, s3, 8
	v_mov_b32_e32 v2, s3
	v_or_b32_e32 v2, 0x1000, v2
	s_waitcnt lgkmcnt(0)
	global_atomic_add v0, v2, v3, s[6:7] sc0
	s_waitcnt vmcnt(0)
	v_readfirstlane_b32 s8, v0
	v_xor_b32_e32 v2, 0x3000, v2
	s_and_b32 s9, s8, 31
	s_lshr_b32 s10, s8, 5
	s_cmp_eq_u32 s9, 31
	s_cbranch_scc0 .Lgs5_wl
	buffer_wbl2 sc1
	s_waitcnt vmcnt(0)
	v_mov_b32_e32 v1, 0x3000
	global_atomic_add v0, v1, v3, s[6:7] sc0
	s_waitcnt vmcnt(0)
	v_readfirstlane_b32 s8, v0
	v_mov_b32_e32 v1, 0x3100
	s_and_b32 s9, s8, 7
	s_lshr_b32 s11, s8, 3
	s_cmp_eq_u32 s9, 7
	s_cbranch_scc0 .Lgs5_wt
	global_atomic_add v1, v3, s[6:7]
	s_branch .Lgs5_td

; #define SEAM(k) do { if (IN(k) && IN((k) + 1)) grid.sync(); } while (0)
; __global__ void __launch_bounds__(512, 2) mega_fwd(Args args) {
;     ...
;     SEAM(5);
.LBB0_1068:
	s_cmp_gt_i32 s59, 6
	s_cselect_b64 s[0:1], -1, 0
	s_and_b64 s[4:5], s[4:5], s[0:1]
	s_andn2_b64 vcc, exec, s[4:5]
	s_cbranch_vccnz .LBB0_1080
	v_or_b32_e32 v0, v206, v189
	s_movk_i32 s3, 0x3ff
	v_and_or_b32 v0, v0, s3, v188
	v_cmp_eq_u32_e32 vcc, 0, v0
	s_waitcnt vmcnt(0)
	s_barrier
	s_and_saveexec_b64 s[4:5], vcc
	s_cbranch_execz .LBB0_1079
	v_readlane_b32 s6, v252, 0
	v_readlane_b32 s7, v252, 1
	s_load_dword s8, s[6:7], 0x0
	s_sub_u32 s6, s6, 16
	s_subb_u32 s7, s7, 0
	s_waitcnt lgkmcnt(0)
	s_cmp_lg_u32 s8, 0x100
	s_cbranch_scc1 .Lgs6_cg
	s_load_dwordx2 s[6:7], s[6:7], 0x0
	s_getreg_b32 s3, hwreg(HW_REG_XCC_ID, 0, 4)
	v_mov_b32_e32 v3, 1
	s_mov_b32 s12, 0
	s_lshl_b32 s3, s3, 8
	v_mov_b32_e32 v2, s3
	v_or_b32_e32 v2, 0x1000, v2
	s_waitcnt lgkmcnt(0)
	global_atomic_add v0, v2, v3, s[6:7] sc0
	s_waitcnt vmcnt(0)
	v_readfirstlane_b32 s8, v0
	v_xor_b32_e32 v2, 0x3000, v2
	s_and_b32 s9, s8, 31
	s_lshr_b32 s10, s8, 5
	s_cmp_eq_u32 s9, 31
	s_cbranch_scc0 .Lgs6_wl
	buffer_wbl2 sc1
	s_waitcnt vmcnt(0)
	v_mov_b32_e32 v1, 0x3000
	global_atomic_add v0, v1, v3, s[6:7] sc0
	s_waitcnt vmcnt(0)
	v_readfirstlane_b32 s8, v0
	v_mov_b32_e32 v1, 0x3100
	s_and_b32 s9, s8, 7
	s_lshr_b32 s11, s8, 3
	s_cmp_eq_u32 s9, 7
	s_cbranch_scc0 .Lgs6_wt
	global_atomic_add v1, v3, s[6:7]
	s_branch .Lgs6_td
